# in-loop weight transposes throttled (s_sleep per item) so their HBM traffic is spread across the ff2 phase instead of its first third
# baseline (speedup 1.0000x reference)
.LBB0_2245:
	s_or_b64 exec, exec, s[16:17]
	s_sleep 127
	v_add_u32_e32 v0, s33, v0
	s_movk_i32 s4, 0x177f
	v_cmp_lt_i32_e32 vcc, s4, v0
	v_add_u32_e32 v12, s20, v12
	s_or_b64 s[14:15], vcc, s[14:15]
	v_add_u32_e32 v38, s21, v38
	s_andn2_b64 exec, exec, s[14:15]
	s_cbranch_execz .LBB0_2273
